# up-projection epilogue: ACT stores carry the streaming (nt) cache hint
# speedup vs baseline: 1.0044x; 1.0016x over previous
; __device__ __forceinline__ unsigned cvt_pk_bf16(float lo, float hi) { unsigned r; asm volatile("v_cvt_pk_bf16_f32 %0, %1, %2" : "=v"(r) : "v"(lo), "v"(hi)); return r; }
;     __device__ __forceinline__ void operator()(const f32x4 (&acc)[2][2][4][2], const Unit& u, int wr, int wc, int fr, int fq) const {
;     ...
;             const int cbase = 128 * u.pn + 32 * wc + 16 * n + 4 * fq;
;             const f32x4 w0 = *(const f32x4*)(cw + cbase), w1 = *(const f32x4*)(cw + FF + cbase), w2 = *(const f32x4*)(cw + 2 * FF + cbase), b4 = *(const f32x4*)(cb + cbase);
; #pragma unroll
;             for (int ai = 0; ai < 2; ++ai) {
;                 const int slab = u.pm * 4 + 2 * ai + wr;
;                 f32x4 r1p = (f32x4){0.f, 0.f, 0.f, 0.f}, r2p = (f32x4){0.f, 0.f, 0.f, 0.f};
; #pragma unroll
;                 for (int m = 0; m < 4; ++m) {
;                     const f32x4 g = acc[ai][1][m][n] * rs[ai][m], v = acc[ai][0][m][n] * rs[ai][m];
;                     f32x4 r1, r2, a;
; #pragma unroll
;                     for (int e = 0; e < 4; ++e) { r1[e] = __shfl(g[e], src1); r2[e] = __shfl(g[e], src2); }
; #pragma unroll
;                     for (int e = 0; e < 4; ++e) {
;                         const float p1 = fr >= 1 ? r1[e] : r1p[e], p2 = fr >= 2 ? r2[e] : r2p[e];
;                         const float gg = b4[e] + w0[e] * p2 + w1[e] * p1 + w2[e] * g[e];
;                         a[e] = gg * __builtin_amdgcn_rcpf(1.f + __expf(-gg)) * v[e];
;                     }
;                     r1p = r1; r2p = r2;
;                     const size_t row = (size_t)(u.pm * BM + ai * HALF + wr * 64 + m * 16 + fr);
;                     if (m == 0 && fr < 2) {
;                         *(f32x4*)(GF + (size_t)(slab * 2 + fr) * FF + cbase) = g; *(f32x4*)(VF + (size_t)(slab * 2 + fr) * FF + cbase) = v;
;                     } else {
;                         typedef unsigned u32x2v __attribute__((ext_vector_type(2)));
;                         u32x2v w; w.x = cvt_pk_bf16(a[0], a[1]); w.y = cvt_pk_bf16(a[2], a[3]);
;                         *(u32x2v*)(ACT + row * FF + cbase) = w;
.LBB0_53:
	s_or_b64 exec, exec, s[10:11]
	s_nop 0
	v_or_b32_e32 v70, 16, v156
	v_ashrrev_i32_e32 v71, 31, v70
	v_lshlrev_b64 v[70:71], 2, v[70:71]
	v_lshl_add_u64 v[72:73], s[60:61], 0, v[70:71]
	v_lshl_add_u64 v[70:71], s[62:63], 0, v[70:71]
	global_load_dwordx4 v[66:69], v[166:167], off offset:64
	global_load_dwordx4 v[78:81], v[72:73], off
	global_load_dwordx4 v[74:77], v[70:71], off
	s_nop 0
	global_load_dwordx4 v[70:73], v[164:165], off offset:64
	v_mov_b32_e32 v163, v162
	v_mov_b32_e32 v120, v162
	v_mov_b32_e32 v121, v162
	v_pk_mul_f32 v[84:85], v[60:61], v[120:121]
	v_pk_mul_f32 v[82:83], v[58:59], v[162:163]
	s_nop 1
	v_mov_b32_dpp v101, v82 row_ror:1 row_mask:0xf bank_mask:0xf
	v_mov_b32_dpp v91, v82 row_ror:2 row_mask:0xf bank_mask:0xf
	v_mov_b32_dpp v115, v83 row_ror:1 row_mask:0xf bank_mask:0xf
	v_mov_b32_dpp v93, v83 row_ror:2 row_mask:0xf bank_mask:0xf
	v_mov_b32_dpp v117, v84 row_ror:1 row_mask:0xf bank_mask:0xf
	v_mov_b32_dpp v95, v84 row_ror:2 row_mask:0xf bank_mask:0xf
	v_mov_b32_dpp v119, v85 row_ror:1 row_mask:0xf bank_mask:0xf
	v_mov_b32_dpp v103, v85 row_ror:2 row_mask:0xf bank_mask:0xf
	v_pk_mul_f32 v[60:61], v[64:65], v[120:121]
	v_pk_mul_f32 v[58:59], v[62:63], v[162:163]
	s_and_saveexec_b64 s[10:11], s[42:43]
	s_xor_b64 s[10:11], exec, s[10:11]
	s_cbranch_execz .LBB0_55
	v_mov_b32_e32 v62, v85
	s_waitcnt vmcnt(2)
	v_mov_b32_e32 v63, v81
	s_waitcnt vmcnt(1)
	v_mov_b32_e32 v118, v77
	s_waitcnt lgkmcnt(1)
	v_pk_mul_f32 v[62:63], v[62:63], v[118:119]
	s_waitcnt vmcnt(0) lgkmcnt(0)
	v_fma_f32 v64, v69, v103, v73
	v_add_f32_e32 v63, v63, v64
	v_add_f32_e32 v62, v62, v63
	v_mul_f32_e32 v63, 0xbfb8aa3b, v62
	v_exp_f32_e32 v63, v63
	v_mov_b32_e32 v85, v80
	v_mov_b32_e32 v116, v76
	v_mov_b32_e32 v114, v75
	v_add_f32_e32 v63, 1.0, v63
	v_rcp_f32_e32 v63, v63
	v_mov_b32_e32 v100, v74
	v_mul_f32_e32 v62, v62, v63
	v_mul_f32_e32 v64, v61, v62
	v_pk_mul_f32 v[62:63], v[84:85], v[116:117]
	v_fma_f32 v61, v68, v95, v72
	v_add_f32_e32 v61, v63, v61
	v_add_f32_e32 v61, v62, v61
	v_mul_f32_e32 v62, 0xbfb8aa3b, v61
	v_exp_f32_e32 v62, v62
	v_fma_f32 v63, v67, v93, v71
	v_add_f32_e32 v62, 1.0, v62
	v_rcp_f32_e32 v62, v62
	s_nop 0
	v_mul_f32_e32 v61, v61, v62
	v_mul_f32_e32 v62, v60, v61
	v_mov_b32_e32 v60, v83
	v_mov_b32_e32 v61, v79
	v_pk_mul_f32 v[60:61], v[60:61], v[114:115]
	v_mov_b32_e32 v83, v78
	v_add_f32_e32 v61, v61, v63
	v_add_f32_e32 v60, v60, v61
	v_mul_f32_e32 v61, 0xbfb8aa3b, v60
	v_exp_f32_e32 v61, v61
	v_fma_f32 v63, v66, v91, v70
	v_add_f32_e32 v61, 1.0, v61
	v_rcp_f32_e32 v61, v61
	s_nop 0
	v_mul_f32_e32 v60, v60, v61
	v_mul_f32_e32 v59, v59, v60
	v_pk_mul_f32 v[60:61], v[82:83], v[100:101]
	s_nop 0
	v_add_f32_e32 v61, v61, v63
	v_add_f32_e32 v60, v60, v61
	v_mul_f32_e32 v61, 0xbfb8aa3b, v60
	v_exp_f32_e32 v61, v61
	s_nop 0
	v_add_f32_e32 v61, 1.0, v61
	v_rcp_f32_e32 v61, v61
	s_nop 0
	v_mul_f32_e32 v60, v60, v61
	v_mul_f32_e32 v58, v58, v60
	v_mov_b64_e32 v[60:61], s[48:49]
	v_mad_i64_i32 v[60:61], s[12:13], v160, s17, v[60:61]
	v_cvt_pk_bf16_f32 v58, v58, v59
	v_cvt_pk_bf16_f32 v59, v62, v64
	v_lshl_add_u64 v[60:61], v[156:157], 1, v[60:61]
	v_mov_b32_e32 v64, v77
	v_mov_b32_e32 v62, v75
	s_nop 1
	v_permlane16_swap_b32_e32 v220, v58
	v_permlane16_swap_b32_e32 v221, v59
	v_mov_b32_e32 v222, v58
	v_mov_b32_e32 v223, v59
	v_add_co_u32_e64 v60, s[98:99], v60, v205
	s_nop 1
	v_addc_co_u32_e64 v61, s[98:99], 0, v61, s[98:99]
	global_store_dwordx4 v[60:61], v[220:223], off nt

; __device__ __forceinline__ unsigned cvt_pk_bf16(float lo, float hi) { unsigned r; asm volatile("v_cvt_pk_bf16_f32 %0, %1, %2" : "=v"(r) : "v"(lo), "v"(hi)); return r; }
;     __device__ __forceinline__ void operator()(const f32x4 (&acc)[2][2][4][2], const Unit& u, int wr, int wc, int fr, int fq) const {
;     ...
;                     const f32x4 g = acc[ai][1][m][n] * rs[ai][m], v = acc[ai][0][m][n] * rs[ai][m];
;                     f32x4 r1, r2, a;
; #pragma unroll
;                     for (int e = 0; e < 4; ++e) { r1[e] = __shfl(g[e], src1); r2[e] = __shfl(g[e], src2); }
; #pragma unroll
;                     for (int e = 0; e < 4; ++e) {
;                         const float p1 = fr >= 1 ? r1[e] : r1p[e], p2 = fr >= 2 ? r2[e] : r2p[e];
;                         const float gg = b4[e] + w0[e] * p2 + w1[e] * p1 + w2[e] * g[e];
;                         a[e] = gg * __builtin_amdgcn_rcpf(1.f + __expf(-gg)) * v[e];
;                     }
;                     r1p = r1; r2p = r2;
;                     const size_t row = (size_t)(u.pm * BM + ai * HALF + wr * 64 + m * 16 + fr);
;                     if (m == 0 && fr < 2) {
;                         *(f32x4*)(GF + (size_t)(slab * 2 + fr) * FF + cbase) = g; *(f32x4*)(VF + (size_t)(slab * 2 + fr) * FF + cbase) = v;
;                     } else {
;                         typedef unsigned u32x2v __attribute__((ext_vector_type(2)));
;                         u32x2v w; w.x = cvt_pk_bf16(a[0], a[1]); w.y = cvt_pk_bf16(a[2], a[3]);
;                         *(u32x2v*)(ACT + row * FF + cbase) = w;
.LBB0_57:
	s_or_b64 exec, exec, s[10:11]
	v_mov_b32_e32 v58, v142
	v_mov_b32_e32 v59, v142
	v_pk_mul_f32 v[56:57], v[56:57], v[58:59]
	s_nop 1
	v_mov_b32_dpp v83, v57 row_ror:1 row_mask:0xf bank_mask:0xf
	v_mov_b32_dpp v114, v57 row_ror:2 row_mask:0xf bank_mask:0xf
	v_mov_b32_e32 v60, v57
	s_waitcnt vmcnt(2)
	v_mov_b32_e32 v61, v81
	v_pk_mul_f32 v[52:53], v[52:53], v[58:59]
	s_waitcnt lgkmcnt(1)
	v_cndmask_b32_e64 v65, v83, v119, s[40:41]
	s_waitcnt lgkmcnt(0)
	v_cndmask_b32_e64 v57, v103, v114, s[42:43]
	v_pk_mul_f32 v[60:61], v[60:61], v[64:65]
	s_waitcnt vmcnt(0)
	v_fma_f32 v57, v69, v57, v73
	v_add_f32_e32 v57, v61, v57
	v_add_f32_e32 v60, v60, v57
	v_mul_f32_e32 v57, 0xbfb8aa3b, v60
	v_exp_f32_e32 v57, v57
	v_mov_b32_dpp v61, v56 row_ror:1 row_mask:0xf bank_mask:0xf
	v_mov_b32_dpp v103, v56 row_ror:2 row_mask:0xf bank_mask:0xf
	v_mov_b32_e32 v143, v142
	v_add_f32_e32 v57, 1.0, v57
	v_rcp_f32_e32 v58, v57
	s_waitcnt lgkmcnt(1)
	v_cndmask_b32_e64 v77, v61, v117, s[40:41]
	v_mov_b32_e32 v57, v80
	s_waitcnt lgkmcnt(0)
	v_cndmask_b32_e64 v59, v95, v103, s[42:43]
	v_pk_mul_f32 v[56:57], v[56:57], v[76:77]
	v_fma_f32 v59, v68, v59, v72
	v_add_f32_e32 v57, v57, v59
	v_add_f32_e32 v59, v56, v57
	v_pk_mul_f32 v[54:55], v[54:55], v[142:143]
	v_mul_f32_e32 v56, 0xbfb8aa3b, v59
	s_nop 1
	v_mov_b32_dpp v85, v55 row_ror:1 row_mask:0xf bank_mask:0xf
	v_mov_b32_dpp v100, v55 row_ror:2 row_mask:0xf bank_mask:0xf
	v_exp_f32_e32 v56, v56
	v_mul_f32_e32 v57, v60, v58
	v_mov_b32_dpp v82, v54 row_ror:1 row_mask:0xf bank_mask:0xf
	v_mov_b32_dpp v84, v54 row_ror:2 row_mask:0xf bank_mask:0xf
	v_add_f32_e32 v56, 1.0, v56
	v_mul_f32_e32 v53, v53, v57
	v_rcp_f32_e32 v58, v56
	s_waitcnt lgkmcnt(3)
	v_cndmask_b32_e64 v63, v85, v115, s[40:41]
	v_mov_b32_e32 v56, v55
	v_mov_b32_e32 v57, v79
	s_waitcnt lgkmcnt(2)
	v_cndmask_b32_e64 v55, v93, v100, s[42:43]
	v_pk_mul_f32 v[56:57], v[56:57], v[62:63]
	v_fma_f32 v55, v67, v55, v71
	v_add_f32_e32 v55, v57, v55
	v_add_f32_e32 v56, v56, v55
	v_mul_f32_e32 v55, 0xbfb8aa3b, v56
	v_exp_f32_e32 v57, v55
	s_waitcnt lgkmcnt(1)
	v_cndmask_b32_e64 v75, v82, v101, s[40:41]
	v_mov_b32_e32 v55, v78
	s_waitcnt lgkmcnt(0)
	v_cndmask_b32_e64 v60, v91, v84, s[42:43]
	v_pk_mul_f32 v[54:55], v[54:55], v[74:75]
	v_fma_f32 v60, v66, v60, v70
	v_add_f32_e32 v55, v55, v60
	v_add_f32_e32 v54, v54, v55
	v_mul_f32_e32 v55, 0xbfb8aa3b, v54
	v_exp_f32_e32 v55, v55
	v_add_f32_e32 v57, 1.0, v57
	v_rcp_f32_e32 v57, v57
	v_pk_mul_f32 v[50:51], v[50:51], v[142:143]
	v_add_f32_e32 v55, 1.0, v55
	v_rcp_f32_e32 v55, v55
	v_mul_f32_e32 v56, v56, v57
	v_mul_f32_e32 v58, v59, v58
	v_mul_f32_e32 v51, v51, v56
	v_mul_f32_e32 v54, v54, v55
	v_mul_f32_e32 v50, v50, v54
	v_mul_f32_e32 v52, v52, v58
	v_cvt_pk_bf16_f32 v50, v50, v51
	v_cvt_pk_bf16_f32 v51, v52, v53
	s_nop 1
	v_permlane16_swap_b32_e32 v206, v50
	v_permlane16_swap_b32_e32 v207, v51
	v_mov_b32_e32 v220, v206
	v_mov_b32_e32 v221, v207
	v_mov_b32_e32 v222, v50
	v_mov_b32_e32 v223, v51
	v_add_co_u32_e64 v122, s[98:99], v122, v205
	s_nop 1
	v_addc_co_u32_e64 v123, s[98:99], 0, v123, s[98:99]
	global_store_dwordx4 v[122:123], v[220:223], off nt
	v_mov_b32_e32 v50, v136
	v_mov_b32_e32 v51, v136
	v_pk_mul_f32 v[48:49], v[48:49], v[50:51]
	s_nop 1
	v_mov_b32_dpp v55, v49 row_ror:1 row_mask:0xf bank_mask:0xf
	v_mov_b32_dpp v59, v49 row_ror:2 row_mask:0xf bank_mask:0xf
	v_mov_b32_e32 v52, v49
	v_mov_b32_e32 v53, v81
	v_mov_b32_dpp v60, v48 row_ror:2 row_mask:0xf bank_mask:0xf
	s_waitcnt lgkmcnt(2)
	v_cndmask_b32_e64 v65, v55, v83, s[40:41]
	s_waitcnt lgkmcnt(1)
	v_cndmask_b32_e64 v49, v114, v59, s[42:43]
	v_pk_mul_f32 v[52:53], v[52:53], v[64:65]
	v_fma_f32 v49, v69, v49, v73
	v_add_f32_e32 v49, v53, v49
	v_add_f32_e32 v52, v52, v49
	v_mul_f32_e32 v49, 0xbfb8aa3b, v52
	v_exp_f32_e32 v49, v49
	v_mov_b32_dpp v53, v48 row_ror:1 row_mask:0xf bank_mask:0xf
	v_pk_mul_f32 v[44:45], v[44:45], v[50:51]
	s_waitcnt lgkmcnt(1)
	v_cndmask_b32_e64 v51, v103, v60, s[42:43]
	v_add_f32_e32 v49, 1.0, v49
	v_rcp_f32_e32 v50, v49
	s_waitcnt lgkmcnt(0)
	v_cndmask_b32_e64 v77, v53, v61, s[40:41]
	v_mov_b32_e32 v49, v80
	v_pk_mul_f32 v[48:49], v[48:49], v[76:77]
	v_fma_f32 v51, v68, v51, v72
	v_add_f32_e32 v49, v49, v51
	v_mov_b32_e32 v137, v136
	v_add_f32_e32 v51, v48, v49
	v_pk_mul_f32 v[46:47], v[46:47], v[136:137]
	v_mul_f32_e32 v48, 0xbfb8aa3b, v51
	s_nop 1
	v_mov_b32_dpp v57, v47 row_ror:1 row_mask:0xf bank_mask:0xf
	v_mov_b32_dpp v58, v47 row_ror:2 row_mask:0xf bank_mask:0xf
	v_exp_f32_e32 v48, v48
	v_mul_f32_e32 v49, v52, v50
	v_mov_b32_dpp v54, v46 row_ror:1 row_mask:0xf bank_mask:0xf
	v_mov_b32_dpp v56, v46 row_ror:2 row_mask:0xf bank_mask:0xf
	v_add_f32_e32 v48, 1.0, v48
	v_mul_f32_e32 v45, v45, v49
	v_rcp_f32_e32 v50, v48
	s_waitcnt lgkmcnt(3)
	v_cndmask_b32_e64 v63, v57, v85, s[40:41]
	v_mov_b32_e32 v48, v47
	v_mov_b32_e32 v49, v79
	s_waitcnt lgkmcnt(2)
	v_cndmask_b32_e64 v47, v100, v58, s[42:43]
	v_pk_mul_f32 v[48:49], v[48:49], v[62:63]
	v_fma_f32 v47, v67, v47, v71
	v_add_f32_e32 v47, v49, v47
	v_add_f32_e32 v48, v48, v47
	v_mul_f32_e32 v47, 0xbfb8aa3b, v48
	v_exp_f32_e32 v49, v47
	s_waitcnt lgkmcnt(1)
	v_cndmask_b32_e64 v75, v54, v82, s[40:41]
	v_mov_b32_e32 v47, v78
	s_waitcnt lgkmcnt(0)
; __device__ __forceinline__ unsigned cvt_pk_bf16(float lo, float hi) { unsigned r; asm volatile("v_cvt_pk_bf16_f32 %0, %1, %2" : "=v"(r) : "v"(lo), "v"(hi)); return r; }
;     __device__ __forceinline__ void operator()(const f32x4 (&acc)[2][2][4][2], const Unit& u, int wr, int wc, int fr, int fq) const {
;     ...
;                     const f32x4 g = acc[ai][1][m][n] * rs[ai][m], v = acc[ai][0][m][n] * rs[ai][m];
;                     f32x4 r1, r2, a;
; #pragma unroll
;                     for (int e = 0; e < 4; ++e) { r1[e] = __shfl(g[e], src1); r2[e] = __shfl(g[e], src2); }
; #pragma unroll
;                     for (int e = 0; e < 4; ++e) {
;                         const float p1 = fr >= 1 ? r1[e] : r1p[e], p2 = fr >= 2 ? r2[e] : r2p[e];
;                         const float gg = b4[e] + w0[e] * p2 + w1[e] * p1 + w2[e] * g[e];
;                         a[e] = gg * __builtin_amdgcn_rcpf(1.f + __expf(-gg)) * v[e];
;                     }
;                     r1p = r1; r2p = r2;
;                     const size_t row = (size_t)(u.pm * BM + ai * HALF + wr * 64 + m * 16 + fr);
;                     if (m == 0 && fr < 2) {
;                         *(f32x4*)(GF + (size_t)(slab * 2 + fr) * FF + cbase) = g; *(f32x4*)(VF + (size_t)(slab * 2 + fr) * FF + cbase) = v;
;                     } else {
;                         typedef unsigned u32x2v __attribute__((ext_vector_type(2)));
;                         u32x2v w; w.x = cvt_pk_bf16(a[0], a[1]); w.y = cvt_pk_bf16(a[2], a[3]);
;                         *(u32x2v*)(ACT + row * FF + cbase) = w;
;                     }
;                     if (m == 3 && fr >= 14) *(f32x4*)(GL + (size_t)(slab * 2 + fr - 14) * FF + cbase) = g;
	v_cndmask_b32_e64 v52, v84, v56, s[42:43]
	v_pk_mul_f32 v[46:47], v[46:47], v[74:75]
	v_fma_f32 v52, v66, v52, v70
	v_add_f32_e32 v47, v47, v52
	v_add_f32_e32 v46, v46, v47
	v_mul_f32_e32 v47, 0xbfb8aa3b, v46
	v_exp_f32_e32 v47, v47
	v_add_f32_e32 v49, 1.0, v49
	v_rcp_f32_e32 v49, v49
	v_pk_mul_f32 v[42:43], v[42:43], v[136:137]
	v_add_f32_e32 v47, 1.0, v47
	v_rcp_f32_e32 v47, v47
	v_mul_f32_e32 v48, v48, v49
	v_mul_f32_e32 v50, v51, v50
	v_mul_f32_e32 v43, v43, v48
	v_mul_f32_e32 v46, v46, v47
	v_mul_f32_e32 v42, v42, v46
	v_mul_f32_e32 v44, v44, v50
	v_cvt_pk_bf16_f32 v42, v42, v43
	v_cvt_pk_bf16_f32 v43, v44, v45
	s_nop 1
	v_permlane16_swap_b32_e32 v208, v42
	v_permlane16_swap_b32_e32 v209, v43
	v_mov_b32_e32 v220, v208
	v_mov_b32_e32 v221, v209
	v_mov_b32_e32 v222, v42
	v_mov_b32_e32 v223, v43
	v_add_co_u32_e64 v108, s[98:99], v108, v205
	s_nop 1
	v_addc_co_u32_e64 v109, s[98:99], 0, v109, s[98:99]
	global_store_dwordx4 v[108:109], v[220:223], off nt
	v_mov_b32_e32 v42, v134
	v_mov_b32_e32 v43, v134
	v_pk_mul_f32 v[40:41], v[40:41], v[42:43]
	s_nop 1
	v_mov_b32_dpp v44, v41 row_ror:1 row_mask:0xf bank_mask:0xf
	v_mov_b32_dpp v50, v41 row_ror:2 row_mask:0xf bank_mask:0xf
	v_mov_b32_e32 v45, v81
	v_mov_b32_dpp v51, v40 row_ror:2 row_mask:0xf bank_mask:0xf
	v_pk_mul_f32 v[36:37], v[36:37], v[42:43]
	s_waitcnt lgkmcnt(2)
	v_cndmask_b32_e64 v65, v44, v55, s[40:41]
	v_mov_b32_e32 v44, v41
	s_waitcnt lgkmcnt(1)
	v_cndmask_b32_e64 v50, v59, v50, s[42:43]
	v_pk_mul_f32 v[44:45], v[44:45], v[64:65]
	v_fma_f32 v50, v69, v50, v73
	v_add_f32_e32 v45, v45, v50
	v_add_f32_e32 v44, v44, v45
	v_mul_f32_e32 v45, 0xbfb8aa3b, v44
	v_exp_f32_e32 v45, v45
	v_mov_b32_dpp v50, v40 row_ror:1 row_mask:0xf bank_mask:0xf
	v_mov_b32_e32 v43, v80
	v_mov_b32_e32 v135, v134
	v_add_f32_e32 v42, 1.0, v45
	v_rcp_f32_e32 v45, v42
	s_waitcnt lgkmcnt(0)
	v_cndmask_b32_e64 v77, v50, v53, s[40:41]
	v_mov_b32_e32 v42, v40
	v_cndmask_b32_e64 v50, v60, v51, s[42:43]
	v_pk_mul_f32 v[42:43], v[42:43], v[76:77]
	v_fma_f32 v50, v68, v50, v72
	v_add_f32_e32 v43, v43, v50
	v_add_f32_e32 v50, v42, v43
	v_pk_mul_f32 v[38:39], v[38:39], v[134:135]
	v_mul_f32_e32 v42, 0xbfb8aa3b, v50
	s_nop 1
	v_mov_b32_dpp v48, v39 row_ror:1 row_mask:0xf bank_mask:0xf
	v_mov_b32_dpp v49, v39 row_ror:2 row_mask:0xf bank_mask:0xf
	v_exp_f32_e32 v42, v42
	v_mul_f32_e32 v43, v44, v45
	v_mov_b32_dpp v46, v38 row_ror:1 row_mask:0xf bank_mask:0xf
	v_mov_b32_dpp v47, v38 row_ror:2 row_mask:0xf bank_mask:0xf
	v_add_f32_e32 v42, 1.0, v42
	v_mul_f32_e32 v37, v37, v43
	v_rcp_f32_e32 v44, v42
	s_waitcnt lgkmcnt(3)
	v_cndmask_b32_e64 v63, v48, v57, s[40:41]
	v_mov_b32_e32 v42, v39
	v_mov_b32_e32 v43, v79
	s_waitcnt lgkmcnt(2)
	v_cndmask_b32_e64 v45, v58, v49, s[42:43]
	v_pk_mul_f32 v[42:43], v[42:43], v[62:63]
	v_fma_f32 v45, v67, v45, v71
	v_add_f32_e32 v43, v43, v45
	v_add_f32_e32 v45, v42, v43
	v_mul_f32_e32 v42, 0xbfb8aa3b, v45
	v_exp_f32_e32 v48, v42
	s_waitcnt lgkmcnt(1)
	v_cndmask_b32_e64 v75, v46, v54, s[40:41]
	v_mov_b32_e32 v42, v38
	v_mov_b32_e32 v43, v78
	s_waitcnt lgkmcnt(0)
	v_cndmask_b32_e64 v46, v56, v47, s[42:43]
	v_pk_mul_f32 v[42:43], v[42:43], v[74:75]
	v_fma_f32 v46, v66, v46, v70
	v_add_f32_e32 v43, v43, v46
	v_add_f32_e32 v42, v42, v43
	v_mul_f32_e32 v43, 0xbfb8aa3b, v42
	v_exp_f32_e32 v43, v43
	v_add_f32_e32 v46, 1.0, v48
	v_rcp_f32_e32 v46, v46
	v_mul_f32_e32 v44, v50, v44
	v_add_f32_e32 v43, 1.0, v43
	v_rcp_f32_e32 v43, v43
	v_pk_mul_f32 v[34:35], v[34:35], v[134:135]
	v_mul_f32_e32 v36, v36, v44
	v_mul_f32_e32 v44, v45, v46
	v_mul_f32_e32 v42, v42, v43
	v_mul_f32_e32 v35, v35, v44
	v_mul_f32_e32 v34, v34, v42
	v_cvt_pk_bf16_f32 v34, v34, v35
	v_cvt_pk_bf16_f32 v35, v36, v37
	s_nop 1
	v_permlane16_swap_b32_e32 v210, v34
	v_permlane16_swap_b32_e32 v211, v35
	v_mov_b32_e32 v220, v210
	v_mov_b32_e32 v221, v211
	v_mov_b32_e32 v222, v34
	v_mov_b32_e32 v223, v35
	v_add_co_u32_e64 v110, s[98:99], v110, v205
	s_nop 1
	v_addc_co_u32_e64 v111, s[98:99], 0, v111, s[98:99]
	global_store_dwordx4 v[110:111], v[220:223], off nt
	s_and_saveexec_b64 s[10:11], s[44:45]
	s_cbranch_execz .LBB0_59
	global_store_dwordx4 v[106:107], v[38:41], off offset:64
.LBB0_59:
	s_or_b64 exec, exec, s[10:11]
	v_mov_b32_e32 v103, v102
	v_mov_b32_e32 v42, v102
	v_mov_b32_e32 v43, v102
	v_pk_mul_f32 v[36:37], v[28:29], v[42:43]
	v_pk_mul_f32 v[34:35], v[26:27], v[102:103]
	s_nop 1
	v_mov_b32_dpp v75, v34 row_ror:1 row_mask:0xf bank_mask:0xf
	v_mov_b32_dpp v38, v34 row_ror:2 row_mask:0xf bank_mask:0xf
	v_mov_b32_dpp v63, v35 row_ror:1 row_mask:0xf bank_mask:0xf
	v_mov_b32_dpp v39, v35 row_ror:2 row_mask:0xf bank_mask:0xf
	v_mov_b32_dpp v77, v36 row_ror:1 row_mask:0xf bank_mask:0xf
	v_mov_b32_dpp v40, v36 row_ror:2 row_mask:0xf bank_mask:0xf
	v_mov_b32_dpp v65, v37 row_ror:1 row_mask:0xf bank_mask:0xf
	v_mov_b32_dpp v41, v37 row_ror:2 row_mask:0xf bank_mask:0xf
	v_pk_mul_f32 v[28:29], v[32:33], v[42:43]
	v_pk_mul_f32 v[26:27], v[30:31], v[102:103]
	s_and_saveexec_b64 s[10:11], s[42:43]
	s_xor_b64 s[10:11], exec, s[10:11]
	s_cbranch_execz .LBB0_61
	v_mov_b32_e32 v30, v37
	v_mov_b32_e32 v31, v81
	s_waitcnt lgkmcnt(1)
	v_pk_mul_f32 v[30:31], v[30:31], v[64:65]
	s_waitcnt lgkmcnt(0)
	v_fma_f32 v32, v69, v41, v73
	v_add_f32_e32 v31, v31, v32
	v_add_f32_e32 v30, v30, v31
	v_mul_f32_e32 v31, 0xbfb8aa3b, v30
	v_exp_f32_e32 v31, v31
	v_mov_b32_e32 v37, v80
	v_add_f32_e32 v31, 1.0, v31
	v_rcp_f32_e32 v31, v31
	s_nop 0
	v_mul_f32_e32 v30, v30, v31
	v_mul_f32_e32 v32, v29, v30
	v_pk_mul_f32 v[30:31], v[36:37], v[76:77]
	v_fma_f32 v29, v68, v40, v72
	v_add_f32_e32 v29, v31, v29
	v_add_f32_e32 v29, v30, v29
	v_mul_f32_e32 v30, 0xbfb8aa3b, v29
	v_exp_f32_e32 v30, v30
	v_fma_f32 v31, v67, v39, v71
	v_add_f32_e32 v30, 1.0, v30
	v_rcp_f32_e32 v30, v30
	s_nop 0
	v_mul_f32_e32 v29, v29, v30
	v_mul_f32_e32 v30, v28, v29
	v_mov_b32_e32 v28, v35
	v_mov_b32_e32 v29, v79
	v_pk_mul_f32 v[28:29], v[28:29], v[62:63]
	v_mov_b32_e32 v35, v78
	v_add_f32_e32 v29, v29, v31
	v_add_f32_e32 v28, v28, v29
	v_mul_f32_e32 v29, 0xbfb8aa3b, v28
	v_exp_f32_e32 v29, v29
	v_fma_f32 v31, v66, v38, v70
	v_add_f32_e32 v29, 1.0, v29
	v_rcp_f32_e32 v29, v29
	s_nop 0
	v_mul_f32_e32 v28, v28, v29
	v_mul_f32_e32 v27, v27, v28
	v_pk_mul_f32 v[28:29], v[34:35], v[74:75]
	s_nop 0
	v_add_f32_e32 v29, v29, v31
	v_add_f32_e32 v28, v28, v29
	v_mul_f32_e32 v29, 0xbfb8aa3b, v28
	v_exp_f32_e32 v29, v29
	s_nop 0
	v_add_f32_e32 v29, 1.0, v29
	v_rcp_f32_e32 v29, v29
	s_nop 0
	v_mul_f32_e32 v28, v28, v29
	v_mul_f32_e32 v26, v26, v28
	v_mov_b64_e32 v[28:29], s[48:49]
	v_mad_i64_i32 v[28:29], s[12:13], v180, s17, v[28:29]
	v_cvt_pk_bf16_f32 v26, v26, v27
	v_cvt_pk_bf16_f32 v27, v30, v32
	v_lshl_add_u64 v[28:29], v[156:157], 1, v[28:29]
	s_nop 1
	v_permlane16_swap_b32_e32 v212, v26
	v_permlane16_swap_b32_e32 v213, v27
	v_mov_b32_e32 v220, v212
	v_mov_b32_e32 v221, v213
	v_mov_b32_e32 v222, v26
	v_mov_b32_e32 v223, v27
	v_add_co_u32_e64 v28, s[98:99], v28, v205
	s_nop 1
	v_addc_co_u32_e64 v29, s[98:99], 0, v29, s[98:99]
	global_store_dwordx4 v[28:29], v[220:223], off nt

; __device__ __forceinline__ unsigned cvt_pk_bf16(float lo, float hi) { unsigned r; asm volatile("v_cvt_pk_bf16_f32 %0, %1, %2" : "=v"(r) : "v"(lo), "v"(hi)); return r; }
;     __device__ __forceinline__ void operator()(const f32x4 (&acc)[2][2][4][2], const Unit& u, int wr, int wc, int fr, int fq) const {
;     ...
;                     const f32x4 g = acc[ai][1][m][n] * rs[ai][m], v = acc[ai][0][m][n] * rs[ai][m];
;                     f32x4 r1, r2, a;
; #pragma unroll
;                     for (int e = 0; e < 4; ++e) { r1[e] = __shfl(g[e], src1); r2[e] = __shfl(g[e], src2); }
; #pragma unroll
;                     for (int e = 0; e < 4; ++e) {
;                         const float p1 = fr >= 1 ? r1[e] : r1p[e], p2 = fr >= 2 ? r2[e] : r2p[e];
;                         const float gg = b4[e] + w0[e] * p2 + w1[e] * p1 + w2[e] * g[e];
;                         a[e] = gg * __builtin_amdgcn_rcpf(1.f + __expf(-gg)) * v[e];
;                     }
;                     r1p = r1; r2p = r2;
;                     const size_t row = (size_t)(u.pm * BM + ai * HALF + wr * 64 + m * 16 + fr);
;                     if (m == 0 && fr < 2) {
;                         *(f32x4*)(GF + (size_t)(slab * 2 + fr) * FF + cbase) = g; *(f32x4*)(VF + (size_t)(slab * 2 + fr) * FF + cbase) = v;
;                     } else {
;                         typedef unsigned u32x2v __attribute__((ext_vector_type(2)));
;                         u32x2v w; w.x = cvt_pk_bf16(a[0], a[1]); w.y = cvt_pk_bf16(a[2], a[3]);
;                         *(u32x2v*)(ACT + row * FF + cbase) = w;
.LBB0_63:
	s_or_b64 exec, exec, s[10:11]
	s_nop 0
	v_mov_b32_e32 v26, v94
	v_mov_b32_e32 v27, v94
	v_pk_mul_f32 v[24:25], v[24:25], v[26:27]
	s_nop 1
	v_mov_b32_dpp v31, v25 row_ror:1 row_mask:0xf bank_mask:0xf
	v_mov_b32_dpp v35, v25 row_ror:2 row_mask:0xf bank_mask:0xf
	v_mov_b32_e32 v28, v25
	v_mov_b32_e32 v29, v81
	v_mov_b32_dpp v36, v24 row_ror:2 row_mask:0xf bank_mask:0xf
	s_waitcnt lgkmcnt(2)
	v_cndmask_b32_e64 v65, v31, v65, s[40:41]
	s_waitcnt lgkmcnt(1)
	v_cndmask_b32_e64 v25, v41, v35, s[42:43]
	v_pk_mul_f32 v[28:29], v[28:29], v[64:65]
	v_fma_f32 v25, v69, v25, v73
	v_add_f32_e32 v25, v29, v25
	v_add_f32_e32 v28, v28, v25
	v_mul_f32_e32 v25, 0xbfb8aa3b, v28
	v_exp_f32_e32 v25, v25
	v_mov_b32_dpp v29, v24 row_ror:1 row_mask:0xf bank_mask:0xf
	v_pk_mul_f32 v[20:21], v[20:21], v[26:27]
	s_waitcnt lgkmcnt(1)
	v_cndmask_b32_e64 v27, v40, v36, s[42:43]
	v_add_f32_e32 v25, 1.0, v25
	v_rcp_f32_e32 v26, v25
	s_waitcnt lgkmcnt(0)
	v_cndmask_b32_e64 v77, v29, v77, s[40:41]
	v_mov_b32_e32 v25, v80
	v_pk_mul_f32 v[24:25], v[24:25], v[76:77]
	v_fma_f32 v27, v68, v27, v72
	v_add_f32_e32 v25, v25, v27
	v_mov_b32_e32 v95, v94
	v_add_f32_e32 v27, v24, v25
	v_pk_mul_f32 v[22:23], v[22:23], v[94:95]
	v_mul_f32_e32 v24, 0xbfb8aa3b, v27
	s_nop 1
	v_mov_b32_dpp v33, v23 row_ror:1 row_mask:0xf bank_mask:0xf
	v_mov_b32_dpp v34, v23 row_ror:2 row_mask:0xf bank_mask:0xf
	v_exp_f32_e32 v24, v24
	v_mul_f32_e32 v25, v28, v26
	v_mov_b32_dpp v30, v22 row_ror:1 row_mask:0xf bank_mask:0xf
	v_mov_b32_dpp v32, v22 row_ror:2 row_mask:0xf bank_mask:0xf
	v_add_f32_e32 v24, 1.0, v24
	v_mul_f32_e32 v21, v21, v25
	v_rcp_f32_e32 v26, v24
	s_waitcnt lgkmcnt(3)
	v_cndmask_b32_e64 v63, v33, v63, s[40:41]
	v_mov_b32_e32 v24, v23
	v_mov_b32_e32 v25, v79
	s_waitcnt lgkmcnt(2)
	v_cndmask_b32_e64 v23, v39, v34, s[42:43]
	v_pk_mul_f32 v[24:25], v[24:25], v[62:63]
	v_fma_f32 v23, v67, v23, v71
	v_add_f32_e32 v23, v25, v23
	v_add_f32_e32 v24, v24, v23
	v_mul_f32_e32 v23, 0xbfb8aa3b, v24
	v_exp_f32_e32 v25, v23
	s_waitcnt lgkmcnt(1)
	v_cndmask_b32_e64 v75, v30, v75, s[40:41]
	v_mov_b32_e32 v23, v78
	s_waitcnt lgkmcnt(0)
	v_cndmask_b32_e64 v28, v38, v32, s[42:43]
	v_pk_mul_f32 v[22:23], v[22:23], v[74:75]
	v_fma_f32 v28, v66, v28, v70
	v_add_f32_e32 v23, v23, v28
	v_add_f32_e32 v22, v22, v23
	v_mul_f32_e32 v23, 0xbfb8aa3b, v22
	v_exp_f32_e32 v23, v23
	v_add_f32_e32 v25, 1.0, v25
	v_rcp_f32_e32 v25, v25
	v_pk_mul_f32 v[18:19], v[18:19], v[94:95]
	v_add_f32_e32 v23, 1.0, v23
	v_rcp_f32_e32 v23, v23
	v_mul_f32_e32 v24, v24, v25
	v_mul_f32_e32 v26, v27, v26
	v_mul_f32_e32 v19, v19, v24
	v_mul_f32_e32 v22, v22, v23
	v_mul_f32_e32 v18, v18, v22
	v_mul_f32_e32 v20, v20, v26
	v_cvt_pk_bf16_f32 v18, v18, v19
	v_cvt_pk_bf16_f32 v19, v20, v21
	s_nop 1
	v_permlane16_swap_b32_e32 v214, v18
	v_permlane16_swap_b32_e32 v215, v19
	v_mov_b32_e32 v220, v214
	v_mov_b32_e32 v221, v215
	v_mov_b32_e32 v222, v18
	v_mov_b32_e32 v223, v19
	v_add_co_u32_e64 v98, s[98:99], v98, v205
	s_nop 1
	v_addc_co_u32_e64 v99, s[98:99], 0, v99, s[98:99]
	global_store_dwordx4 v[98:99], v[220:223], off nt
	v_mov_b32_e32 v18, v92
	v_mov_b32_e32 v19, v92
	v_pk_mul_f32 v[16:17], v[16:17], v[18:19]
	s_nop 1
	v_mov_b32_dpp v23, v17 row_ror:1 row_mask:0xf bank_mask:0xf
	v_mov_b32_dpp v27, v17 row_ror:2 row_mask:0xf bank_mask:0xf
	v_mov_b32_e32 v20, v17
	v_mov_b32_e32 v21, v81
	v_mov_b32_dpp v28, v16 row_ror:2 row_mask:0xf bank_mask:0xf
	s_waitcnt lgkmcnt(2)
	v_cndmask_b32_e64 v65, v23, v31, s[40:41]
	s_waitcnt lgkmcnt(1)
	v_cndmask_b32_e64 v17, v35, v27, s[42:43]
	v_pk_mul_f32 v[20:21], v[20:21], v[64:65]
	v_fma_f32 v17, v69, v17, v73
	v_add_f32_e32 v17, v21, v17
	v_add_f32_e32 v20, v20, v17
	v_mul_f32_e32 v17, 0xbfb8aa3b, v20
	v_exp_f32_e32 v17, v17
	v_mov_b32_dpp v21, v16 row_ror:1 row_mask:0xf bank_mask:0xf
	v_pk_mul_f32 v[12:13], v[12:13], v[18:19]
	s_waitcnt lgkmcnt(1)
	v_cndmask_b32_e64 v19, v36, v28, s[42:43]
	v_add_f32_e32 v17, 1.0, v17
	v_rcp_f32_e32 v18, v17
	s_waitcnt lgkmcnt(0)
	v_cndmask_b32_e64 v77, v21, v29, s[40:41]
	v_mov_b32_e32 v17, v80
	v_pk_mul_f32 v[16:17], v[16:17], v[76:77]
	v_fma_f32 v19, v68, v19, v72
	v_add_f32_e32 v17, v17, v19
	v_mov_b32_e32 v93, v92
	v_add_f32_e32 v19, v16, v17
	v_pk_mul_f32 v[14:15], v[14:15], v[92:93]
	v_mul_f32_e32 v16, 0xbfb8aa3b, v19
	s_nop 1
	v_mov_b32_dpp v25, v15 row_ror:1 row_mask:0xf bank_mask:0xf
	v_mov_b32_dpp v26, v15 row_ror:2 row_mask:0xf bank_mask:0xf
	v_exp_f32_e32 v16, v16
	v_mul_f32_e32 v17, v20, v18
	v_mov_b32_dpp v22, v14 row_ror:1 row_mask:0xf bank_mask:0xf
	v_mov_b32_dpp v24, v14 row_ror:2 row_mask:0xf bank_mask:0xf
	v_add_f32_e32 v16, 1.0, v16
	v_mul_f32_e32 v13, v13, v17
	v_rcp_f32_e32 v18, v16
	s_waitcnt lgkmcnt(3)
; __device__ __forceinline__ unsigned cvt_pk_bf16(float lo, float hi) { unsigned r; asm volatile("v_cvt_pk_bf16_f32 %0, %1, %2" : "=v"(r) : "v"(lo), "v"(hi)); return r; }
;     __device__ __forceinline__ void operator()(const f32x4 (&acc)[2][2][4][2], const Unit& u, int wr, int wc, int fr, int fq) const {
;     ...
;                     const f32x4 g = acc[ai][1][m][n] * rs[ai][m], v = acc[ai][0][m][n] * rs[ai][m];
;                     f32x4 r1, r2, a;
; #pragma unroll
;                     for (int e = 0; e < 4; ++e) { r1[e] = __shfl(g[e], src1); r2[e] = __shfl(g[e], src2); }
; #pragma unroll
;                     for (int e = 0; e < 4; ++e) {
;                         const float p1 = fr >= 1 ? r1[e] : r1p[e], p2 = fr >= 2 ? r2[e] : r2p[e];
;                         const float gg = b4[e] + w0[e] * p2 + w1[e] * p1 + w2[e] * g[e];
;                         a[e] = gg * __builtin_amdgcn_rcpf(1.f + __expf(-gg)) * v[e];
;                     }
;                     r1p = r1; r2p = r2;
;                     const size_t row = (size_t)(u.pm * BM + ai * HALF + wr * 64 + m * 16 + fr);
;                     if (m == 0 && fr < 2) {
;                         *(f32x4*)(GF + (size_t)(slab * 2 + fr) * FF + cbase) = g; *(f32x4*)(VF + (size_t)(slab * 2 + fr) * FF + cbase) = v;
;                     } else {
;                         typedef unsigned u32x2v __attribute__((ext_vector_type(2)));
;                         u32x2v w; w.x = cvt_pk_bf16(a[0], a[1]); w.y = cvt_pk_bf16(a[2], a[3]);
;                         *(u32x2v*)(ACT + row * FF + cbase) = w;
;                     }
;                     if (m == 3 && fr >= 14) *(f32x4*)(GL + (size_t)(slab * 2 + fr - 14) * FF + cbase) = g;
	v_cndmask_b32_e64 v63, v25, v33, s[40:41]
	v_mov_b32_e32 v16, v15
	v_mov_b32_e32 v17, v79
	s_waitcnt lgkmcnt(2)
	v_cndmask_b32_e64 v15, v34, v26, s[42:43]
	v_pk_mul_f32 v[16:17], v[16:17], v[62:63]
	v_fma_f32 v15, v67, v15, v71
	v_add_f32_e32 v15, v17, v15
	v_add_f32_e32 v16, v16, v15
	v_mul_f32_e32 v15, 0xbfb8aa3b, v16
	v_exp_f32_e32 v17, v15
	s_waitcnt lgkmcnt(1)
	v_cndmask_b32_e64 v75, v22, v30, s[40:41]
	v_mov_b32_e32 v15, v78
	s_waitcnt lgkmcnt(0)
	v_cndmask_b32_e64 v20, v32, v24, s[42:43]
	v_pk_mul_f32 v[14:15], v[14:15], v[74:75]
	v_fma_f32 v20, v66, v20, v70
	v_add_f32_e32 v15, v15, v20
	v_add_f32_e32 v14, v14, v15
	v_mul_f32_e32 v15, 0xbfb8aa3b, v14
	v_exp_f32_e32 v15, v15
	v_add_f32_e32 v17, 1.0, v17
	v_rcp_f32_e32 v17, v17
	v_pk_mul_f32 v[10:11], v[10:11], v[92:93]
	v_add_f32_e32 v15, 1.0, v15
	v_rcp_f32_e32 v15, v15
	v_mul_f32_e32 v16, v16, v17
	v_mul_f32_e32 v18, v19, v18
	v_mul_f32_e32 v11, v11, v16
	v_mul_f32_e32 v14, v14, v15
	v_mul_f32_e32 v10, v10, v14
	v_mul_f32_e32 v12, v12, v18
	v_cvt_pk_bf16_f32 v10, v10, v11
	v_cvt_pk_bf16_f32 v11, v12, v13
	s_nop 1
	v_permlane16_swap_b32_e32 v216, v10
	v_permlane16_swap_b32_e32 v217, v11
	v_mov_b32_e32 v220, v216
	v_mov_b32_e32 v221, v217
	v_mov_b32_e32 v222, v10
	v_mov_b32_e32 v223, v11
	v_add_co_u32_e64 v96, s[98:99], v96, v205
	s_nop 1
	v_addc_co_u32_e64 v97, s[98:99], 0, v97, s[98:99]
	global_store_dwordx4 v[96:97], v[220:223], off nt
	v_mov_b32_e32 v10, v90
	v_mov_b32_e32 v11, v90
	v_pk_mul_f32 v[8:9], v[8:9], v[10:11]
	s_nop 1
	v_mov_b32_dpp v12, v9 row_ror:1 row_mask:0xf bank_mask:0xf
	v_mov_b32_dpp v18, v9 row_ror:2 row_mask:0xf bank_mask:0xf
	v_mov_b32_e32 v13, v81
	v_mov_b32_dpp v19, v8 row_ror:2 row_mask:0xf bank_mask:0xf
	v_pk_mul_f32 v[4:5], v[4:5], v[10:11]
	s_waitcnt lgkmcnt(2)
	v_cndmask_b32_e64 v65, v12, v23, s[40:41]
	v_mov_b32_e32 v12, v9
	s_waitcnt lgkmcnt(1)
	v_cndmask_b32_e64 v18, v27, v18, s[42:43]
	v_pk_mul_f32 v[12:13], v[12:13], v[64:65]
	v_fma_f32 v18, v69, v18, v73
	v_add_f32_e32 v13, v13, v18
	v_add_f32_e32 v12, v12, v13
	v_mul_f32_e32 v13, 0xbfb8aa3b, v12
	v_exp_f32_e32 v13, v13
	v_mov_b32_dpp v18, v8 row_ror:1 row_mask:0xf bank_mask:0xf
	v_mov_b32_e32 v11, v80
	v_mov_b32_e32 v91, v90
	v_add_f32_e32 v10, 1.0, v13
	v_rcp_f32_e32 v13, v10
	s_waitcnt lgkmcnt(0)
	v_cndmask_b32_e64 v77, v18, v21, s[40:41]
	v_mov_b32_e32 v10, v8
	v_cndmask_b32_e64 v18, v28, v19, s[42:43]
	v_pk_mul_f32 v[10:11], v[10:11], v[76:77]
	v_fma_f32 v18, v68, v18, v72
	v_add_f32_e32 v11, v11, v18
	v_add_f32_e32 v18, v10, v11
	v_pk_mul_f32 v[6:7], v[6:7], v[90:91]
	v_mul_f32_e32 v10, 0xbfb8aa3b, v18
	s_nop 1
	v_mov_b32_dpp v16, v7 row_ror:1 row_mask:0xf bank_mask:0xf
	v_mov_b32_dpp v17, v7 row_ror:2 row_mask:0xf bank_mask:0xf
	v_exp_f32_e32 v10, v10
	v_mul_f32_e32 v11, v12, v13
	v_mov_b32_dpp v14, v6 row_ror:1 row_mask:0xf bank_mask:0xf
	v_mov_b32_dpp v15, v6 row_ror:2 row_mask:0xf bank_mask:0xf
	v_add_f32_e32 v10, 1.0, v10
	v_mul_f32_e32 v5, v5, v11
	v_rcp_f32_e32 v12, v10
	s_waitcnt lgkmcnt(3)
	v_cndmask_b32_e64 v63, v16, v25, s[40:41]
	v_mov_b32_e32 v10, v7
	v_mov_b32_e32 v11, v79
	s_waitcnt lgkmcnt(2)
	v_cndmask_b32_e64 v13, v26, v17, s[42:43]
	v_pk_mul_f32 v[10:11], v[10:11], v[62:63]
	v_fma_f32 v13, v67, v13, v71
	v_add_f32_e32 v11, v11, v13
	v_add_f32_e32 v13, v10, v11
	v_mul_f32_e32 v10, 0xbfb8aa3b, v13
	v_exp_f32_e32 v16, v10
	s_waitcnt lgkmcnt(1)
	v_cndmask_b32_e64 v75, v14, v22, s[40:41]
	v_mov_b32_e32 v10, v6
	v_mov_b32_e32 v11, v78
	s_waitcnt lgkmcnt(0)
	v_cndmask_b32_e64 v14, v24, v15, s[42:43]
	v_pk_mul_f32 v[10:11], v[10:11], v[74:75]
	v_fmac_f32_e32 v70, v66, v14
	v_add_f32_e32 v11, v11, v70
	v_add_f32_e32 v10, v10, v11
	v_mul_f32_e32 v11, 0xbfb8aa3b, v10
	v_exp_f32_e32 v11, v11
	v_add_f32_e32 v14, 1.0, v16
	v_rcp_f32_e32 v14, v14
	v_mul_f32_e32 v12, v18, v12
	v_add_f32_e32 v11, 1.0, v11
	v_rcp_f32_e32 v11, v11
	v_pk_mul_f32 v[2:3], v[2:3], v[90:91]
	v_mul_f32_e32 v4, v4, v12
	v_mul_f32_e32 v12, v13, v14
	v_mul_f32_e32 v10, v10, v11
	v_mul_f32_e32 v3, v3, v12
	v_mul_f32_e32 v2, v2, v10
	v_cvt_pk_bf16_f32 v2, v2, v3
	v_cvt_pk_bf16_f32 v3, v4, v5
	s_nop 1
	v_permlane16_swap_b32_e32 v218, v2
	v_permlane16_swap_b32_e32 v219, v3
	v_mov_b32_e32 v220, v218
	v_mov_b32_e32 v221, v219
	v_mov_b32_e32 v222, v2
	v_mov_b32_e32 v223, v3
	v_add_co_u32_e64 v88, s[98:99], v88, v205
	s_nop 1
	v_addc_co_u32_e64 v89, s[98:99], 0, v89, s[98:99]
	global_store_dwordx4 v[88:89], v[220:223], off nt
	s_and_saveexec_b64 s[10:11], s[44:45]
	s_cbranch_execz .LBB0_65
	global_store_dwordx4 v[86:87], v[6:9], off offset:64
